# weight conversion: batches of 6 adjacent tiles per iteration (1.5 KB contiguous source rows per block)
# speedup vs baseline: 1.0118x; 1.0097x over previous
; __device__ __forceinline__ int fresh_bid() { int t; asm volatile("s_mov_b32 %0, %1" : "=s"(t) : "s"(blockIdx.x)); return t; }
; __device__ __forceinline__ void phase_convert(const Ctx& a, int l, LAS unsigned char* lds) {
;     ...
;     for (int j = 0; j < 10; ++j) {
;         CJob c = get_job(j, a, l);
;         const int nkt = c.K / 64, nnt = c.Ntot / 64, ntile = nkt * nnt;
;         int first = (int)((fresh_bid() + gridDim.x - (base % gridDim.x)) % gridDim.x);
;         float pv[8];
;     ...
;         if (first < ntile) CV_LOAD(first);
;         for (int i = first; i < ntile; i += gridDim.x) {
.LBB0_717:
	s_mov_b32 s30, s2
	s_load_dword s9, s[74:75], 0x0
	s_mul_i32 s46, s26, s51
	s_add_i32 s52, s46, 5
	s_mul_hi_u32 s52, s52, 0x2aaaaaab
	v_cvt_f32_u32_e32 v22, s51
	s_waitcnt lgkmcnt(0)
	v_cvt_f32_u32_e32 v21, s9
	s_sub_i32 s26, 0, s9
	v_rcp_iflag_f32_e32 v21, v21
	s_nop 0
	v_mul_f32_e32 v21, 0x4f7ffffe, v21
	v_cvt_u32_f32_e32 v23, v21
	v_rcp_iflag_f32_e32 v21, v22
	v_readfirstlane_b32 s42, v23
	s_mul_i32 s26, s26, s42
	s_mul_hi_u32 s26, s42, s26
	s_add_i32 s42, s42, s26
	s_mul_hi_u32 s26, s48, s42
	s_mul_i32 s26, s26, s9
	s_sub_i32 s26, s48, s26
	s_sub_i32 s43, s26, s9
	s_cmp_ge_u32 s26, s9
	s_cselect_b32 s26, s43, s26
	s_sub_i32 s43, s26, s9
	s_cmp_ge_u32 s26, s9
	s_cselect_b32 s26, s43, s26
	s_add_i32 s30, s9, s30
	s_sub_i32 s26, s30, s26
	s_mul_hi_u32 s30, s26, s42
	s_mul_i32 s30, s30, s9
	s_sub_i32 s26, s26, s30
	s_sub_i32 s30, s26, s9
	s_cmp_ge_u32 s26, s9
	s_cselect_b32 s26, s30, s26
	s_sub_i32 s30, s26, s9
	s_cmp_ge_u32 s26, s9
	s_cselect_b32 s53, s30, s26
	s_cmp_lt_i32 s53, s52
	s_cselect_b64 s[44:45], -1, 0
	s_cmp_ge_i32 s53, s52
	s_cbranch_scc1 .LBB0_693
	s_waitcnt vmcnt(0) lgkmcnt(0)
	v_mul_f32_e32 v21, 0x4f7ffffe, v21
	v_cvt_u32_f32_e32 v21, v21
	s_sub_i32 s26, 0, s51
	v_readfirstlane_b32 s44, v21
	v_readfirstlane_b32 s56, v14
	v_readfirstlane_b32 s57, v15
	v_readfirstlane_b32 s58, v16
	v_readfirstlane_b32 s59, v17
	s_xor_b64 s[42:43], s[36:37], -1
	v_cmp_ne_u64_e64 s[36:37], 0, v[16:17]
	s_nop 3
	s_mul_i32 s26, s26, s44
	s_mul_hi_u32 s26, s44, s26
	s_add_i32 s54, s44, s26
	s_lshl_b64 s[44:45], s[40:41], 1
	s_add_u32 s38, s38, s44
	s_addc_u32 s39, s39, s45
	s_lshl_b64 s[40:41], s[0:1], 5
	v_lshlrev_b32_e32 v141, 2, v2
	v_add_u32_e32 v32, 0x10400, v20
	v_mov_b32_e32 v42, 1.0
	v_mov_b32_e32 v43, 1.0
	v_mov_b32_e32 v44, 1.0
	v_mov_b32_e32 v45, 1.0
	v_mov_b32_e32 v46, 1.0
	v_mov_b32_e32 v47, 1.0
	v_mov_b32_e32 v48, 1.0
	v_mov_b32_e32 v49, 1.0
	v_mov_b32_e32 v58, 1.0
	v_mov_b32_e32 v59, 1.0
	v_mov_b32_e32 v60, 1.0
	v_mov_b32_e32 v61, 1.0
	v_mov_b32_e32 v62, 1.0
	v_mov_b32_e32 v63, 1.0
	v_mov_b32_e32 v64, 1.0
	v_mov_b32_e32 v65, 1.0
	v_mov_b32_e32 v74, 1.0
	v_mov_b32_e32 v75, 1.0
	v_mov_b32_e32 v76, 1.0
	v_mov_b32_e32 v77, 1.0
	v_mov_b32_e32 v78, 1.0
	v_mov_b32_e32 v79, 1.0
	v_mov_b32_e32 v80, 1.0
	v_mov_b32_e32 v81, 1.0
	v_mov_b32_e32 v90, 1.0
	v_mov_b32_e32 v91, 1.0
	v_mov_b32_e32 v92, 1.0
	v_mov_b32_e32 v93, 1.0
	v_mov_b32_e32 v94, 1.0
	v_mov_b32_e32 v95, 1.0
	v_mov_b32_e32 v96, 1.0
	v_mov_b32_e32 v97, 1.0
	v_mov_b32_e32 v106, 1.0
	v_mov_b32_e32 v107, 1.0
	v_mov_b32_e32 v108, 1.0
	v_mov_b32_e32 v109, 1.0
	v_mov_b32_e32 v110, 1.0
	v_mov_b32_e32 v111, 1.0
	v_mov_b32_e32 v112, 1.0
	v_mov_b32_e32 v113, 1.0
	v_mov_b32_e32 v122, 1.0
	v_mov_b32_e32 v123, 1.0
	v_mov_b32_e32 v124, 1.0
	v_mov_b32_e32 v125, 1.0
	v_mov_b32_e32 v126, 1.0
	v_mov_b32_e32 v127, 1.0
	v_mov_b32_e32 v128, 1.0
	v_mov_b32_e32 v129, 1.0
	s_mov_b32 s60, 0
	s_mul_i32 s30, s53, 6
	s_cmp_ge_i32 s30, s46
	s_cbranch_scc1 .Lcv_isd_a
	s_mul_hi_u32 s26, s30, s54
	s_mul_i32 s55, s26, s51
	s_sub_i32 s55, s30, s55
	s_sub_i32 s61, s55, s51
	s_add_i32 s62, s26, 1
	s_cmp_ge_u32 s55, s51
	s_cselect_b32 s26, s62, s26
	s_cselect_b32 s55, s61, s55
	s_sub_i32 s61, s55, s51
	s_add_i32 s62, s26, 1
	s_cmp_ge_u32 s55, s51
	s_cselect_b32 s26, s62, s26
	s_cselect_b32 s55, s61, s55
	s_lshl_b32 s61, s26, 6
	s_lshl_b32 s62, s55, 6
	v_add_u32_e32 v130, s62, v1
	s_add_i32 s44, s50, -1
	v_min_u32_e32 v136, s44, v130
	v_add_u32_e32 v137, s61, v2
	v_mad_u32_u24 v136, v137, s0, v136
	v_lshlrev_b32_e32 v136, 2, v136
	s_mov_b64 s[44:45], s[56:57]
	global_load_dword v34, v136, s[44:45] nt
	s_add_u32 s44, s44, s40
	s_addc_u32 s45, s45, s41
	global_load_dword v35, v136, s[44:45] nt
	s_add_u32 s44, s44, s40
	s_addc_u32 s45, s45, s41
	global_load_dword v36, v136, s[44:45] nt
	s_add_u32 s44, s44, s40
	s_addc_u32 s45, s45, s41
	global_load_dword v37, v136, s[44:45] nt
	s_add_u32 s44, s44, s40
	s_addc_u32 s45, s45, s41
	global_load_dword v38, v136, s[44:45] nt
	s_add_u32 s44, s44, s40
	s_addc_u32 s45, s45, s41
	global_load_dword v39, v136, s[44:45] nt
	s_add_u32 s44, s44, s40
	s_addc_u32 s45, s45, s41
	global_load_dword v40, v136, s[44:45] nt
	s_add_u32 s44, s44, s40
	s_addc_u32 s45, s45, s41
	global_load_dword v41, v136, s[44:45] nt
	s_cmp_eq_u64 s[36:37], 0
	s_cbranch_scc1 .Lcv_ng_a_0
	s_lshl_b32 s61, s61, 2
	s_add_u32 s44, s58, s61
	s_addc_u32 s45, s59, 0
	global_load_dword v42, v141, s[44:45] offset:0
	global_load_dword v43, v141, s[44:45] offset:32
	global_load_dword v44, v141, s[44:45] offset:64
	global_load_dword v45, v141, s[44:45] offset:96
	global_load_dword v46, v141, s[44:45] offset:128
	global_load_dword v47, v141, s[44:45] offset:160
	global_load_dword v48, v141, s[44:45] offset:192
	global_load_dword v49, v141, s[44:45] offset:224
; __device__ __forceinline__ int fresh_bid() { int t; asm volatile("s_mov_b32 %0, %1" : "=s"(t) : "s"(blockIdx.x)); return t; }
; __device__ __forceinline__ void phase_convert(const Ctx& a, int l, LAS unsigned char* lds) {
;     ...
;         int first = (int)((fresh_bid() + gridDim.x - (base % gridDim.x)) % gridDim.x);
;         float pv[8];
;     ...
;         if (first < ntile) CV_LOAD(first);
;         for (int i = first; i < ntile; i += gridDim.x) {
.Lcv_ng_a_0:
	s_add_i32 s60, s60, 1
	s_add_i32 s30, s30, 1
	s_cmp_ge_i32 s30, s46
	s_cbranch_scc1 .Lcv_isd_a
	s_mul_hi_u32 s26, s30, s54
	s_mul_i32 s55, s26, s51
	s_sub_i32 s55, s30, s55
	s_sub_i32 s61, s55, s51
	s_add_i32 s62, s26, 1
	s_cmp_ge_u32 s55, s51
	s_cselect_b32 s26, s62, s26
	s_cselect_b32 s55, s61, s55
	s_sub_i32 s61, s55, s51
	s_add_i32 s62, s26, 1
	s_cmp_ge_u32 s55, s51
	s_cselect_b32 s26, s62, s26
	s_cselect_b32 s55, s61, s55
	s_lshl_b32 s61, s26, 6
	s_lshl_b32 s62, s55, 6
	v_add_u32_e32 v131, s62, v1
	s_add_i32 s44, s50, -1
	v_min_u32_e32 v136, s44, v131
	v_add_u32_e32 v137, s61, v2
	v_mad_u32_u24 v136, v137, s0, v136
	v_lshlrev_b32_e32 v136, 2, v136
	s_mov_b64 s[44:45], s[56:57]
	global_load_dword v50, v136, s[44:45] nt
	s_add_u32 s44, s44, s40
	s_addc_u32 s45, s45, s41
	global_load_dword v51, v136, s[44:45] nt
	s_add_u32 s44, s44, s40
	s_addc_u32 s45, s45, s41
	global_load_dword v52, v136, s[44:45] nt
	s_add_u32 s44, s44, s40
	s_addc_u32 s45, s45, s41
	global_load_dword v53, v136, s[44:45] nt
	s_add_u32 s44, s44, s40
	s_addc_u32 s45, s45, s41
	global_load_dword v54, v136, s[44:45] nt
	s_add_u32 s44, s44, s40
	s_addc_u32 s45, s45, s41
	global_load_dword v55, v136, s[44:45] nt
	s_add_u32 s44, s44, s40
	s_addc_u32 s45, s45, s41
	global_load_dword v56, v136, s[44:45] nt
	s_add_u32 s44, s44, s40
	s_addc_u32 s45, s45, s41
	global_load_dword v57, v136, s[44:45] nt
	s_cmp_eq_u64 s[36:37], 0
	s_cbranch_scc1 .Lcv_ng_a_1
	s_lshl_b32 s61, s61, 2
	s_add_u32 s44, s58, s61
	s_addc_u32 s45, s59, 0
	global_load_dword v58, v141, s[44:45] offset:0
	global_load_dword v59, v141, s[44:45] offset:32
	global_load_dword v60, v141, s[44:45] offset:64
	global_load_dword v61, v141, s[44:45] offset:96
	global_load_dword v62, v141, s[44:45] offset:128
	global_load_dword v63, v141, s[44:45] offset:160
	global_load_dword v64, v141, s[44:45] offset:192
	global_load_dword v65, v141, s[44:45] offset:224
.Lcv_ng_a_1:
	s_add_i32 s60, s60, 1
	s_add_i32 s30, s30, 1
	s_cmp_ge_i32 s30, s46
	s_cbranch_scc1 .Lcv_isd_a
	s_mul_hi_u32 s26, s30, s54
	s_mul_i32 s55, s26, s51
	s_sub_i32 s55, s30, s55
	s_sub_i32 s61, s55, s51
	s_add_i32 s62, s26, 1
	s_cmp_ge_u32 s55, s51
	s_cselect_b32 s26, s62, s26
	s_cselect_b32 s55, s61, s55
	s_sub_i32 s61, s55, s51
	s_add_i32 s62, s26, 1
	s_cmp_ge_u32 s55, s51
	s_cselect_b32 s26, s62, s26
	s_cselect_b32 s55, s61, s55
	s_lshl_b32 s61, s26, 6
	s_lshl_b32 s62, s55, 6
	v_add_u32_e32 v132, s62, v1
	s_add_i32 s44, s50, -1
	v_min_u32_e32 v136, s44, v132
	v_add_u32_e32 v137, s61, v2
	v_mad_u32_u24 v136, v137, s0, v136
	v_lshlrev_b32_e32 v136, 2, v136
	s_mov_b64 s[44:45], s[56:57]
	global_load_dword v66, v136, s[44:45] nt
	s_add_u32 s44, s44, s40
	s_addc_u32 s45, s45, s41
	global_load_dword v67, v136, s[44:45] nt
	s_add_u32 s44, s44, s40
	s_addc_u32 s45, s45, s41
	global_load_dword v68, v136, s[44:45] nt
	s_add_u32 s44, s44, s40
	s_addc_u32 s45, s45, s41
	global_load_dword v69, v136, s[44:45] nt
	s_add_u32 s44, s44, s40
	s_addc_u32 s45, s45, s41
	global_load_dword v70, v136, s[44:45] nt
	s_add_u32 s44, s44, s40
	s_addc_u32 s45, s45, s41
	global_load_dword v71, v136, s[44:45] nt
	s_add_u32 s44, s44, s40
	s_addc_u32 s45, s45, s41
	global_load_dword v72, v136, s[44:45] nt
	s_add_u32 s44, s44, s40
	s_addc_u32 s45, s45, s41
	global_load_dword v73, v136, s[44:45] nt
	s_cmp_eq_u64 s[36:37], 0
	s_cbranch_scc1 .Lcv_ng_a_2
	s_lshl_b32 s61, s61, 2
	s_add_u32 s44, s58, s61
	s_addc_u32 s45, s59, 0
	global_load_dword v74, v141, s[44:45] offset:0
	global_load_dword v75, v141, s[44:45] offset:32
	global_load_dword v76, v141, s[44:45] offset:64
	global_load_dword v77, v141, s[44:45] offset:96
	global_load_dword v78, v141, s[44:45] offset:128
	global_load_dword v79, v141, s[44:45] offset:160
	global_load_dword v80, v141, s[44:45] offset:192
	global_load_dword v81, v141, s[44:45] offset:224
.Lcv_ng_a_2:
	s_add_i32 s60, s60, 1
	s_add_i32 s30, s30, 1
	s_cmp_ge_i32 s30, s46
	s_cbranch_scc1 .Lcv_isd_a
	s_mul_hi_u32 s26, s30, s54
	s_mul_i32 s55, s26, s51
	s_sub_i32 s55, s30, s55
	s_sub_i32 s61, s55, s51
	s_add_i32 s62, s26, 1
	s_cmp_ge_u32 s55, s51
	s_cselect_b32 s26, s62, s26
	s_cselect_b32 s55, s61, s55
	s_sub_i32 s61, s55, s51
	s_add_i32 s62, s26, 1
	s_cmp_ge_u32 s55, s51
	s_cselect_b32 s26, s62, s26
	s_cselect_b32 s55, s61, s55
	s_lshl_b32 s61, s26, 6
	s_lshl_b32 s62, s55, 6
	v_add_u32_e32 v133, s62, v1
	s_add_i32 s44, s50, -1
	v_min_u32_e32 v136, s44, v133
	v_add_u32_e32 v137, s61, v2
	v_mad_u32_u24 v136, v137, s0, v136
	v_lshlrev_b32_e32 v136, 2, v136
	s_mov_b64 s[44:45], s[56:57]
	global_load_dword v82, v136, s[44:45] nt
	s_add_u32 s44, s44, s40
	s_addc_u32 s45, s45, s41
	global_load_dword v83, v136, s[44:45] nt
	s_add_u32 s44, s44, s40
	s_addc_u32 s45, s45, s41
	global_load_dword v84, v136, s[44:45] nt
	s_add_u32 s44, s44, s40
	s_addc_u32 s45, s45, s41
	global_load_dword v85, v136, s[44:45] nt
	s_add_u32 s44, s44, s40
	s_addc_u32 s45, s45, s41
	global_load_dword v86, v136, s[44:45] nt
	s_add_u32 s44, s44, s40
	s_addc_u32 s45, s45, s41
	global_load_dword v87, v136, s[44:45] nt
	s_add_u32 s44, s44, s40
	s_addc_u32 s45, s45, s41
	global_load_dword v88, v136, s[44:45] nt
	s_add_u32 s44, s44, s40
	s_addc_u32 s45, s45, s41
	global_load_dword v89, v136, s[44:45] nt
	s_cmp_eq_u64 s[36:37], 0
	s_cbranch_scc1 .Lcv_ng_a_3
	s_lshl_b32 s61, s61, 2
	s_add_u32 s44, s58, s61
	s_addc_u32 s45, s59, 0
	global_load_dword v90, v141, s[44:45] offset:0
	global_load_dword v91, v141, s[44:45] offset:32
	global_load_dword v92, v141, s[44:45] offset:64
	global_load_dword v93, v141, s[44:45] offset:96
	global_load_dword v94, v141, s[44:45] offset:128
	global_load_dword v95, v141, s[44:45] offset:160
	global_load_dword v96, v141, s[44:45] offset:192
	global_load_dword v97, v141, s[44:45] offset:224
; __device__ __forceinline__ int fresh_bid() { int t; asm volatile("s_mov_b32 %0, %1" : "=s"(t) : "s"(blockIdx.x)); return t; }
; __device__ __forceinline__ void phase_convert(const Ctx& a, int l, LAS unsigned char* lds) {
;     ...
;         int first = (int)((fresh_bid() + gridDim.x - (base % gridDim.x)) % gridDim.x);
;         float pv[8];
;     ...
;         if (first < ntile) CV_LOAD(first);
;         for (int i = first; i < ntile; i += gridDim.x) {
.Lcv_ng_a_3:
	s_add_i32 s60, s60, 1
	s_add_i32 s30, s30, 1
	s_cmp_ge_i32 s30, s46
	s_cbranch_scc1 .Lcv_isd_a
	s_mul_hi_u32 s26, s30, s54
	s_mul_i32 s55, s26, s51
	s_sub_i32 s55, s30, s55
	s_sub_i32 s61, s55, s51
	s_add_i32 s62, s26, 1
	s_cmp_ge_u32 s55, s51
	s_cselect_b32 s26, s62, s26
	s_cselect_b32 s55, s61, s55
	s_sub_i32 s61, s55, s51
	s_add_i32 s62, s26, 1
	s_cmp_ge_u32 s55, s51
	s_cselect_b32 s26, s62, s26
	s_cselect_b32 s55, s61, s55
	s_lshl_b32 s61, s26, 6
	s_lshl_b32 s62, s55, 6
	v_add_u32_e32 v134, s62, v1
	s_add_i32 s44, s50, -1
	v_min_u32_e32 v136, s44, v134
	v_add_u32_e32 v137, s61, v2
	v_mad_u32_u24 v136, v137, s0, v136
	v_lshlrev_b32_e32 v136, 2, v136
	s_mov_b64 s[44:45], s[56:57]
	global_load_dword v98, v136, s[44:45] nt
	s_add_u32 s44, s44, s40
	s_addc_u32 s45, s45, s41
	global_load_dword v99, v136, s[44:45] nt
	s_add_u32 s44, s44, s40
	s_addc_u32 s45, s45, s41
	global_load_dword v100, v136, s[44:45] nt
	s_add_u32 s44, s44, s40
	s_addc_u32 s45, s45, s41
	global_load_dword v101, v136, s[44:45] nt
	s_add_u32 s44, s44, s40
	s_addc_u32 s45, s45, s41
	global_load_dword v102, v136, s[44:45] nt
	s_add_u32 s44, s44, s40
	s_addc_u32 s45, s45, s41
	global_load_dword v103, v136, s[44:45] nt
	s_add_u32 s44, s44, s40
	s_addc_u32 s45, s45, s41
	global_load_dword v104, v136, s[44:45] nt
	s_add_u32 s44, s44, s40
	s_addc_u32 s45, s45, s41
	global_load_dword v105, v136, s[44:45] nt
	s_cmp_eq_u64 s[36:37], 0
	s_cbranch_scc1 .Lcv_ng_a_4
	s_lshl_b32 s61, s61, 2
	s_add_u32 s44, s58, s61
	s_addc_u32 s45, s59, 0
	global_load_dword v106, v141, s[44:45] offset:0
	global_load_dword v107, v141, s[44:45] offset:32
	global_load_dword v108, v141, s[44:45] offset:64
	global_load_dword v109, v141, s[44:45] offset:96
	global_load_dword v110, v141, s[44:45] offset:128
	global_load_dword v111, v141, s[44:45] offset:160
	global_load_dword v112, v141, s[44:45] offset:192
	global_load_dword v113, v141, s[44:45] offset:224
.Lcv_ng_a_4:
	s_add_i32 s60, s60, 1
	s_add_i32 s30, s30, 1
	s_cmp_ge_i32 s30, s46
	s_cbranch_scc1 .Lcv_isd_a
	s_mul_hi_u32 s26, s30, s54
	s_mul_i32 s55, s26, s51
	s_sub_i32 s55, s30, s55
	s_sub_i32 s61, s55, s51
	s_add_i32 s62, s26, 1
	s_cmp_ge_u32 s55, s51
	s_cselect_b32 s26, s62, s26
	s_cselect_b32 s55, s61, s55
	s_sub_i32 s61, s55, s51
	s_add_i32 s62, s26, 1
	s_cmp_ge_u32 s55, s51
	s_cselect_b32 s26, s62, s26
	s_cselect_b32 s55, s61, s55
	s_lshl_b32 s61, s26, 6
	s_lshl_b32 s62, s55, 6
	v_add_u32_e32 v135, s62, v1
	s_add_i32 s44, s50, -1
	v_min_u32_e32 v136, s44, v135
	v_add_u32_e32 v137, s61, v2
	v_mad_u32_u24 v136, v137, s0, v136
	v_lshlrev_b32_e32 v136, 2, v136
	s_mov_b64 s[44:45], s[56:57]
	global_load_dword v114, v136, s[44:45] nt
	s_add_u32 s44, s44, s40
	s_addc_u32 s45, s45, s41
	global_load_dword v115, v136, s[44:45] nt
	s_add_u32 s44, s44, s40
	s_addc_u32 s45, s45, s41
	global_load_dword v116, v136, s[44:45] nt
	s_add_u32 s44, s44, s40
	s_addc_u32 s45, s45, s41
	global_load_dword v117, v136, s[44:45] nt
	s_add_u32 s44, s44, s40
	s_addc_u32 s45, s45, s41
	global_load_dword v118, v136, s[44:45] nt
	s_add_u32 s44, s44, s40
	s_addc_u32 s45, s45, s41
	global_load_dword v119, v136, s[44:45] nt
	s_add_u32 s44, s44, s40
	s_addc_u32 s45, s45, s41
	global_load_dword v120, v136, s[44:45] nt
	s_add_u32 s44, s44, s40
	s_addc_u32 s45, s45, s41
	global_load_dword v121, v136, s[44:45] nt
	s_cmp_eq_u64 s[36:37], 0
	s_cbranch_scc1 .Lcv_ng_a_5
	s_lshl_b32 s61, s61, 2
	s_add_u32 s44, s58, s61
	s_addc_u32 s45, s59, 0
	global_load_dword v122, v141, s[44:45] offset:0
	global_load_dword v123, v141, s[44:45] offset:32
	global_load_dword v124, v141, s[44:45] offset:64
	global_load_dword v125, v141, s[44:45] offset:96
	global_load_dword v126, v141, s[44:45] offset:128
	global_load_dword v127, v141, s[44:45] offset:160
	global_load_dword v128, v141, s[44:45] offset:192
	global_load_dword v129, v141, s[44:45] offset:224
.Lcv_ng_a_5:
	s_add_i32 s60, s60, 1
	s_add_i32 s30, s30, 1
.Lcv_isd_a:
	s_cmp_eq_u32 s60, 0
	s_cbranch_scc1 .LBB0_693
	s_waitcnt vmcnt(0)

; __device__ __forceinline__ void phase_convert(const Ctx& a, int l, LAS unsigned char* lds) {
;     ...
;         for (int i = first; i < ntile; i += gridDim.x) {
;             const int kt = i / nnt, ntl = i % nnt, k0 = kt * 64, n0 = ntl * 64;
; #pragma unroll
;             for (int it = 0; it < 8; ++it) tile[((tid >> 6) + it * 8) * 65 + (tid & 63)] = pv[it];
;             __syncthreads();
;             if (i + (int)gridDim.x < ntile) CV_LOAD(i + gridDim.x);
.Lcv_wr_done:
	s_waitcnt lgkmcnt(0)
	s_barrier
	s_mul_i32 s47, s53, 6
	s_mov_b32 s63, s60
	s_add_i32 s53, s53, s9
	s_mov_b32 s60, 0
	s_mul_i32 s30, s53, 6
	s_cmp_ge_i32 s30, s46
	s_cbranch_scc1 .Lcv_isd_b
	s_mul_hi_u32 s26, s30, s54
	s_mul_i32 s55, s26, s51
	s_sub_i32 s55, s30, s55
	s_sub_i32 s61, s55, s51
	s_add_i32 s62, s26, 1
	s_cmp_ge_u32 s55, s51
	s_cselect_b32 s26, s62, s26
	s_cselect_b32 s55, s61, s55
	s_sub_i32 s61, s55, s51
	s_add_i32 s62, s26, 1
	s_cmp_ge_u32 s55, s51
	s_cselect_b32 s26, s62, s26
	s_cselect_b32 s55, s61, s55
	s_lshl_b32 s61, s26, 6
	s_lshl_b32 s62, s55, 6
	v_add_u32_e32 v130, s62, v1
	s_add_i32 s44, s50, -1
	v_min_u32_e32 v136, s44, v130
	v_add_u32_e32 v137, s61, v2
	v_mad_u32_u24 v136, v137, s0, v136
	v_lshlrev_b32_e32 v136, 2, v136
	s_mov_b64 s[44:45], s[56:57]
	global_load_dword v34, v136, s[44:45] nt
	s_add_u32 s44, s44, s40
	s_addc_u32 s45, s45, s41
	global_load_dword v35, v136, s[44:45] nt
	s_add_u32 s44, s44, s40
	s_addc_u32 s45, s45, s41
	global_load_dword v36, v136, s[44:45] nt
	s_add_u32 s44, s44, s40
	s_addc_u32 s45, s45, s41
	global_load_dword v37, v136, s[44:45] nt
	s_add_u32 s44, s44, s40
	s_addc_u32 s45, s45, s41
	global_load_dword v38, v136, s[44:45] nt
	s_add_u32 s44, s44, s40
	s_addc_u32 s45, s45, s41
	global_load_dword v39, v136, s[44:45] nt
	s_add_u32 s44, s44, s40
	s_addc_u32 s45, s45, s41
	global_load_dword v40, v136, s[44:45] nt
	s_add_u32 s44, s44, s40
	s_addc_u32 s45, s45, s41
	global_load_dword v41, v136, s[44:45] nt
	s_cmp_eq_u64 s[36:37], 0
	s_cbranch_scc1 .Lcv_ng_b_0
	s_lshl_b32 s61, s61, 2
	s_add_u32 s44, s58, s61
	s_addc_u32 s45, s59, 0
	global_load_dword v42, v141, s[44:45] offset:0
	global_load_dword v43, v141, s[44:45] offset:32
	global_load_dword v44, v141, s[44:45] offset:64
	global_load_dword v45, v141, s[44:45] offset:96
	global_load_dword v46, v141, s[44:45] offset:128
	global_load_dword v47, v141, s[44:45] offset:160
	global_load_dword v48, v141, s[44:45] offset:192
	global_load_dword v49, v141, s[44:45] offset:224

; __device__ __forceinline__ unsigned cvt_pk(float lo, float hi) { f32x2_t v = {lo, hi}; bf16x2_t b = __builtin_convertvector(v, bf16x2_t); return __builtin_bit_cast(unsigned, b); }
; __device__ __forceinline__ void phase_convert(const Ctx& a, int l, LAS unsigned char* lds) {
;     ...
;             {
;                 int nn = tid >> 3, kc = (tid & 7) * 8, n = n0 + nn, row = n;
;                 if (c.perm) { if (n < FF) row = (n / 128) * 256 + (n % 128); else { int jn = n - FF; row = (jn / 128) * 256 + 128 + (jn % 128); } }
;                 u32x4 w;
;                 w[0] = cvt_pk(tile[(kc + 0) * 65 + nn], tile[(kc + 1) * 65 + nn]);
;                 w[1] = cvt_pk(tile[(kc + 2) * 65 + nn], tile[(kc + 3) * 65 + nn]);
;                 w[2] = cvt_pk(tile[(kc + 4) * 65 + nn], tile[(kc + 5) * 65 + nn]);
;                 w[3] = cvt_pk(tile[(kc + 6) * 65 + nn], tile[(kc + 7) * 65 + nn]);
;                 *(u32x4*)(c.dst + (size_t)row * c.lddst + c.koff + k0 + kc) = w;
;             }
.Lcv_isd_b:
	s_mul_hi_u32 s26, s47, s54
	s_mul_i32 s55, s26, s51
	s_sub_i32 s55, s47, s55
	s_sub_i32 s61, s55, s51
	s_add_i32 s62, s26, 1
	s_cmp_ge_u32 s55, s51
	s_cselect_b32 s26, s62, s26
	s_cselect_b32 s55, s61, s55
	s_sub_i32 s61, s55, s51
	s_add_i32 s62, s26, 1
	s_cmp_ge_u32 s55, s51
	s_cselect_b32 s26, s62, s26
	s_cselect_b32 s55, s61, s55
	s_lshl_b32 s61, s26, 7
	s_lshl_b32 s62, s55, 6
	v_add_u32_e32 v138, s62, v11
	v_cmp_gt_u32_e32 vcc, 0xb00, v138
	v_subrev_u32_e32 v139, 0xb00, v138
	v_cndmask_b32_e32 v139, v139, v138, vcc
	v_lshrrev_b32_e32 v140, 7, v139
	v_and_b32_e32 v139, 0x7f, v139
	v_lshl_or_b32 v139, v140, 8, v139
	v_mov_b32_e32 v140, 0x80
	v_cndmask_b32_e32 v140, v140, v145, vcc
	v_or_b32_e32 v139, v139, v140
	v_cndmask_b32_e64 v138, v138, v139, s[42:43]
	v_mul_u32_u24_e32 v139, s12, v138
	v_lshl_add_u32 v139, v139, 1, v144
	s_add_u32 s44, s38, s61
	s_addc_u32 s45, s39, 0
	v_add_u32_e32 v142, 0x0, v18
	v_add_u32_e32 v143, 0x400, v18
	ds_read2_b32 v[24:25], v142 offset1:65
	ds_read2_b32 v[26:27], v142 offset0:130 offset1:195
	ds_read2_b32 v[28:29], v143 offset0:4 offset1:69
	ds_read2_b32 v[30:31], v143 offset0:134 offset1:199
	s_waitcnt lgkmcnt(0)
	v_cvt_pk_bf16_f32 v4, v24, v25
	v_cvt_pk_bf16_f32 v5, v26, v27
	v_cvt_pk_bf16_f32 v6, v28, v29
	v_cvt_pk_bf16_f32 v7, v30, v31
	global_store_dwordx4 v139, v[4:7], s[44:45]
	s_add_i32 s47, s47, 1
	s_cmp_le_u32 s63, 1
	s_cbranch_scc1 .Lcv_rd_done
	s_mul_hi_u32 s26, s47, s54
	s_mul_i32 s55, s26, s51
	s_sub_i32 s55, s47, s55
	s_sub_i32 s61, s55, s51
	s_add_i32 s62, s26, 1
	s_cmp_ge_u32 s55, s51
	s_cselect_b32 s26, s62, s26
	s_cselect_b32 s55, s61, s55
	s_sub_i32 s61, s55, s51
	s_add_i32 s62, s26, 1
	s_cmp_ge_u32 s55, s51
	s_cselect_b32 s26, s62, s26
	s_cselect_b32 s55, s61, s55
	s_lshl_b32 s61, s26, 7
	s_lshl_b32 s62, s55, 6
	v_add_u32_e32 v138, s62, v11
	v_cmp_gt_u32_e32 vcc, 0xb00, v138
	v_subrev_u32_e32 v139, 0xb00, v138
	v_cndmask_b32_e32 v139, v139, v138, vcc
	v_lshrrev_b32_e32 v140, 7, v139
	v_and_b32_e32 v139, 0x7f, v139
	v_lshl_or_b32 v139, v140, 8, v139
	v_mov_b32_e32 v140, 0x80
	v_cndmask_b32_e32 v140, v140, v145, vcc
	v_or_b32_e32 v139, v139, v140
	v_cndmask_b32_e64 v138, v138, v139, s[42:43]
	v_mul_u32_u24_e32 v139, s12, v138
	v_lshl_add_u32 v139, v139, 1, v144
	s_add_u32 s44, s38, s61
	s_addc_u32 s45, s39, 0
	v_add_u32_e32 v142, 0x4100, v18
	v_add_u32_e32 v143, 0x4500, v18
	ds_read2_b32 v[24:25], v142 offset1:65
	ds_read2_b32 v[26:27], v142 offset0:130 offset1:195
	ds_read2_b32 v[28:29], v143 offset0:4 offset1:69
	ds_read2_b32 v[30:31], v143 offset0:134 offset1:199
	s_waitcnt lgkmcnt(0)
	v_cvt_pk_bf16_f32 v12, v24, v25
	v_cvt_pk_bf16_f32 v13, v26, v27
	v_cvt_pk_bf16_f32 v14, v28, v29
	v_cvt_pk_bf16_f32 v15, v30, v31
	global_store_dwordx4 v139, v[12:15], s[44:45]
	s_add_i32 s47, s47, 1
	s_cmp_le_u32 s63, 2
	s_cbranch_scc1 .Lcv_rd_done
	s_mul_hi_u32 s26, s47, s54
	s_mul_i32 s55, s26, s51
	s_sub_i32 s55, s47, s55
	s_sub_i32 s61, s55, s51
	s_add_i32 s62, s26, 1
	s_cmp_ge_u32 s55, s51
	s_cselect_b32 s26, s62, s26
	s_cselect_b32 s55, s61, s55
	s_sub_i32 s61, s55, s51
	s_add_i32 s62, s26, 1
	s_cmp_ge_u32 s55, s51
	s_cselect_b32 s26, s62, s26
	s_cselect_b32 s55, s61, s55
	s_lshl_b32 s61, s26, 7
	s_lshl_b32 s62, s55, 6
	v_add_u32_e32 v138, s62, v11
	v_cmp_gt_u32_e32 vcc, 0xb00, v138
	v_subrev_u32_e32 v139, 0xb00, v138
	v_cndmask_b32_e32 v139, v139, v138, vcc
	v_lshrrev_b32_e32 v140, 7, v139
	v_and_b32_e32 v139, 0x7f, v139
	v_lshl_or_b32 v139, v140, 8, v139
	v_mov_b32_e32 v140, 0x80
	v_cndmask_b32_e32 v140, v140, v145, vcc
	v_or_b32_e32 v139, v139, v140
	v_cndmask_b32_e64 v138, v138, v139, s[42:43]
	v_mul_u32_u24_e32 v139, s12, v138
	v_lshl_add_u32 v139, v139, 1, v144
	s_add_u32 s44, s38, s61
	s_addc_u32 s45, s39, 0
	v_add_u32_e32 v142, 0x8200, v18
	v_add_u32_e32 v143, 0x8600, v18
	ds_read2_b32 v[24:25], v142 offset1:65
	ds_read2_b32 v[26:27], v142 offset0:130 offset1:195
	ds_read2_b32 v[28:29], v143 offset0:4 offset1:69
	ds_read2_b32 v[30:31], v143 offset0:134 offset1:199
	s_waitcnt lgkmcnt(0)
	v_cvt_pk_bf16_f32 v4, v24, v25
	v_cvt_pk_bf16_f32 v5, v26, v27
	v_cvt_pk_bf16_f32 v6, v28, v29
	v_cvt_pk_bf16_f32 v7, v30, v31
	global_store_dwordx4 v139, v[4:7], s[44:45]
	s_add_i32 s47, s47, 1
	s_cmp_le_u32 s63, 3
	s_cbranch_scc1 .Lcv_rd_done
; __device__ __forceinline__ unsigned cvt_pk(float lo, float hi) { f32x2_t v = {lo, hi}; bf16x2_t b = __builtin_convertvector(v, bf16x2_t); return __builtin_bit_cast(unsigned, b); }
; __device__ __forceinline__ void phase_convert(const Ctx& a, int l, LAS unsigned char* lds) {
;     ...
;             {
;                 int nn = tid >> 3, kc = (tid & 7) * 8, n = n0 + nn, row = n;
;                 if (c.perm) { if (n < FF) row = (n / 128) * 256 + (n % 128); else { int jn = n - FF; row = (jn / 128) * 256 + 128 + (jn % 128); } }
;                 u32x4 w;
;                 w[0] = cvt_pk(tile[(kc + 0) * 65 + nn], tile[(kc + 1) * 65 + nn]);
;                 w[1] = cvt_pk(tile[(kc + 2) * 65 + nn], tile[(kc + 3) * 65 + nn]);
;                 w[2] = cvt_pk(tile[(kc + 4) * 65 + nn], tile[(kc + 5) * 65 + nn]);
;                 w[3] = cvt_pk(tile[(kc + 6) * 65 + nn], tile[(kc + 7) * 65 + nn]);
;                 *(u32x4*)(c.dst + (size_t)row * c.lddst + c.koff + k0 + kc) = w;
;             }
	s_mul_hi_u32 s26, s47, s54
	s_mul_i32 s55, s26, s51
	s_sub_i32 s55, s47, s55
	s_sub_i32 s61, s55, s51
	s_add_i32 s62, s26, 1
	s_cmp_ge_u32 s55, s51
	s_cselect_b32 s26, s62, s26
	s_cselect_b32 s55, s61, s55
	s_sub_i32 s61, s55, s51
	s_add_i32 s62, s26, 1
	s_cmp_ge_u32 s55, s51
	s_cselect_b32 s26, s62, s26
	s_cselect_b32 s55, s61, s55
	s_lshl_b32 s61, s26, 7
	s_lshl_b32 s62, s55, 6
	v_add_u32_e32 v138, s62, v11
	v_cmp_gt_u32_e32 vcc, 0xb00, v138
	v_subrev_u32_e32 v139, 0xb00, v138
	v_cndmask_b32_e32 v139, v139, v138, vcc
	v_lshrrev_b32_e32 v140, 7, v139
	v_and_b32_e32 v139, 0x7f, v139
	v_lshl_or_b32 v139, v140, 8, v139
	v_mov_b32_e32 v140, 0x80
	v_cndmask_b32_e32 v140, v140, v145, vcc
	v_or_b32_e32 v139, v139, v140
	v_cndmask_b32_e64 v138, v138, v139, s[42:43]
	v_mul_u32_u24_e32 v139, s12, v138
	v_lshl_add_u32 v139, v139, 1, v144
	s_add_u32 s44, s38, s61
	s_addc_u32 s45, s39, 0
	v_add_u32_e32 v142, 0xc300, v18
	v_add_u32_e32 v143, 0xc700, v18
	ds_read2_b32 v[24:25], v142 offset1:65
	ds_read2_b32 v[26:27], v142 offset0:130 offset1:195
	ds_read2_b32 v[28:29], v143 offset0:4 offset1:69
	ds_read2_b32 v[30:31], v143 offset0:134 offset1:199
	s_waitcnt lgkmcnt(0)
	v_cvt_pk_bf16_f32 v12, v24, v25
	v_cvt_pk_bf16_f32 v13, v26, v27
	v_cvt_pk_bf16_f32 v14, v28, v29
	v_cvt_pk_bf16_f32 v15, v30, v31
	global_store_dwordx4 v139, v[12:15], s[44:45]
	s_add_i32 s47, s47, 1
	s_cmp_le_u32 s63, 4
	s_cbranch_scc1 .Lcv_rd_done
	s_mul_hi_u32 s26, s47, s54
	s_mul_i32 s55, s26, s51
	s_sub_i32 s55, s47, s55
	s_sub_i32 s61, s55, s51
	s_add_i32 s62, s26, 1
	s_cmp_ge_u32 s55, s51
	s_cselect_b32 s26, s62, s26
	s_cselect_b32 s55, s61, s55
	s_sub_i32 s61, s55, s51
	s_add_i32 s62, s26, 1
	s_cmp_ge_u32 s55, s51
	s_cselect_b32 s26, s62, s26
	s_cselect_b32 s55, s61, s55
	s_lshl_b32 s61, s26, 7
	s_lshl_b32 s62, s55, 6
	v_add_u32_e32 v138, s62, v11
	v_cmp_gt_u32_e32 vcc, 0xb00, v138
	v_subrev_u32_e32 v139, 0xb00, v138
	v_cndmask_b32_e32 v139, v139, v138, vcc
	v_lshrrev_b32_e32 v140, 7, v139
	v_and_b32_e32 v139, 0x7f, v139
	v_lshl_or_b32 v139, v140, 8, v139
	v_mov_b32_e32 v140, 0x80
	v_cndmask_b32_e32 v140, v140, v145, vcc
	v_or_b32_e32 v139, v139, v140
	v_cndmask_b32_e64 v138, v138, v139, s[42:43]
	v_mul_u32_u24_e32 v139, s12, v138
	v_lshl_add_u32 v139, v139, 1, v144
	s_add_u32 s44, s38, s61
	s_addc_u32 s45, s39, 0
	v_add_u32_e32 v142, 0x10400, v18
	v_add_u32_e32 v143, 0x10800, v18
	ds_read2_b32 v[24:25], v142 offset1:65
	ds_read2_b32 v[26:27], v142 offset0:130 offset1:195
	ds_read2_b32 v[28:29], v143 offset0:4 offset1:69
	ds_read2_b32 v[30:31], v143 offset0:134 offset1:199
	s_waitcnt lgkmcnt(0)
	v_cvt_pk_bf16_f32 v4, v24, v25
	v_cvt_pk_bf16_f32 v5, v26, v27
	v_cvt_pk_bf16_f32 v6, v28, v29
	v_cvt_pk_bf16_f32 v7, v30, v31
	global_store_dwordx4 v139, v[4:7], s[44:45]
	s_add_i32 s47, s47, 1
	s_cmp_le_u32 s63, 5
	s_cbranch_scc1 .Lcv_rd_done
	s_mul_hi_u32 s26, s47, s54
	s_mul_i32 s55, s26, s51
	s_sub_i32 s55, s47, s55
	s_sub_i32 s61, s55, s51
	s_add_i32 s62, s26, 1
	s_cmp_ge_u32 s55, s51
	s_cselect_b32 s26, s62, s26
	s_cselect_b32 s55, s61, s55
	s_sub_i32 s61, s55, s51
	s_add_i32 s62, s26, 1
	s_cmp_ge_u32 s55, s51
	s_cselect_b32 s26, s62, s26
	s_cselect_b32 s55, s61, s55
	s_lshl_b32 s61, s26, 7
	s_lshl_b32 s62, s55, 6
	v_add_u32_e32 v138, s62, v11
	v_cmp_gt_u32_e32 vcc, 0xb00, v138
	v_subrev_u32_e32 v139, 0xb00, v138
	v_cndmask_b32_e32 v139, v139, v138, vcc
	v_lshrrev_b32_e32 v140, 7, v139
	v_and_b32_e32 v139, 0x7f, v139
	v_lshl_or_b32 v139, v140, 8, v139
	v_mov_b32_e32 v140, 0x80
	v_cndmask_b32_e32 v140, v140, v145, vcc
	v_or_b32_e32 v139, v139, v140
	v_cndmask_b32_e64 v138, v138, v139, s[42:43]
	v_mul_u32_u24_e32 v139, s12, v138
	v_lshl_add_u32 v139, v139, 1, v144
	s_add_u32 s44, s38, s61
	s_addc_u32 s45, s39, 0
	v_add_u32_e32 v142, 0x14500, v18
	v_add_u32_e32 v143, 0x14900, v18
	ds_read2_b32 v[24:25], v142 offset1:65
	ds_read2_b32 v[26:27], v142 offset0:130 offset1:195
	ds_read2_b32 v[28:29], v143 offset0:4 offset1:69
	ds_read2_b32 v[30:31], v143 offset0:134 offset1:199
	s_waitcnt lgkmcnt(0)
	v_cvt_pk_bf16_f32 v12, v24, v25
	v_cvt_pk_bf16_f32 v13, v26, v27
	v_cvt_pk_bf16_f32 v14, v28, v29
	v_cvt_pk_bf16_f32 v15, v30, v31
	global_store_dwordx4 v139, v[12:15], s[44:45]
	s_add_i32 s47, s47, 1
